# softmax row sums in attnA/attnC step bodies use v_pk_add_f32 on register pairs (15 packed adds + 1 instead of 32 adds per step); f32 accumulation kept, association differs
# baseline (speedup 1.0000x reference)
.LBB0_1057:
	v_cmp_le_i32_e32 vcc, s12, v187
	s_and_saveexec_b64 s[10:11], vcc
	s_cbranch_execz .LBB0_1059
	s_lshl_b32 s12, s12, 15
	s_and_b32 s12, s12, 0x8000
	s_add_i32 s12, s80, s12
	v_add3_u32 v220, s12, v186, v190
	v_add_u32_e32 v221, v220, v199
	v_add_u32_e32 v222, v220, v200
	v_add_u32_e32 v223, v220, v201
	v_add_u32_e32 v224, v220, v202
	v_add_u32_e32 v225, v220, v203
	v_add_u32_e32 v226, v220, v216
	v_add_u32_e32 v227, v220, v217
	v_add_u32_e32 v228, v220, v218
	v_lshrrev_b32_e32 v229, v189, v168
	v_lshrrev_b32_e32 v230, v189, v169
	v_add3_u32 v0, s12, v191, v188
	ds_read_b128 v[2:5], v0
	ds_read_b128 v[8:11], v0 offset:8192
	v_add3_u32 v0, s12, v192, v188
	ds_read_b128 v[12:15], v0
	s_waitcnt lgkmcnt(2)
	v_mfma_f32_32x32x16_bf16 v[112:127], v[2:5], v[156:159], v[16:31]
	ds_read_b128 v[2:5], v0 offset:8192
	s_waitcnt lgkmcnt(2)
	v_mfma_f32_32x32x16_bf16 v[96:111], v[8:11], v[156:159], v[16:31]
	v_add3_u32 v0, s12, v193, v188
	ds_read_b128 v[8:11], v0
	s_waitcnt lgkmcnt(2)
	v_mfma_f32_32x32x16_bf16 v[112:127], v[12:15], v[128:131], v[112:127]
	ds_read_b128 v[12:15], v0 offset:8192
	s_waitcnt lgkmcnt(2)
	v_mfma_f32_32x32x16_bf16 v[96:111], v[2:5], v[128:131], v[96:111]
	v_add3_u32 v0, s12, v194, v188
	ds_read_b128 v[2:5], v0
	s_waitcnt lgkmcnt(2)
	v_mfma_f32_32x32x16_bf16 v[112:127], v[8:11], v[132:135], v[112:127]
	ds_read_b128 v[8:11], v0 offset:8192
	s_waitcnt lgkmcnt(2)
	v_mfma_f32_32x32x16_bf16 v[96:111], v[12:15], v[132:135], v[96:111]
	v_add3_u32 v0, s12, v195, v188
	ds_read_b128 v[12:15], v0
	s_waitcnt lgkmcnt(2)
	v_mfma_f32_32x32x16_bf16 v[112:127], v[2:5], v[136:139], v[112:127]
	ds_read_b128 v[2:5], v0 offset:8192
	s_waitcnt lgkmcnt(2)
	v_mfma_f32_32x32x16_bf16 v[96:111], v[8:11], v[136:139], v[96:111]
	v_add3_u32 v0, s12, v196, v188
	ds_read_b128 v[8:11], v0
	s_waitcnt lgkmcnt(2)
	v_mfma_f32_32x32x16_bf16 v[112:127], v[12:15], v[140:143], v[112:127]
	ds_read_b128 v[12:15], v0 offset:8192
	s_waitcnt lgkmcnt(2)
	v_mfma_f32_32x32x16_bf16 v[96:111], v[2:5], v[140:143], v[96:111]
	v_add3_u32 v0, s12, v197, v188
	ds_read_b128 v[2:5], v0
	s_waitcnt lgkmcnt(2)
	v_mfma_f32_32x32x16_bf16 v[112:127], v[8:11], v[144:147], v[112:127]
	ds_read_b128 v[8:11], v0 offset:8192
	s_waitcnt lgkmcnt(2)
	v_mfma_f32_32x32x16_bf16 v[96:111], v[12:15], v[144:147], v[96:111]
	v_add3_u32 v0, s12, v198, v188
	ds_read_b128 v[12:15], v0
	s_waitcnt lgkmcnt(2)
	v_mfma_f32_32x32x16_bf16 v[112:127], v[2:5], v[148:151], v[112:127]
	ds_read_b128 v[2:5], v0 offset:8192
	s_waitcnt lgkmcnt(2)
	v_mfma_f32_32x32x16_bf16 v[96:111], v[8:11], v[148:151], v[96:111]
	s_waitcnt lgkmcnt(1)
	v_mfma_f32_32x32x16_bf16 v[112:127], v[12:15], v[152:155], v[112:127]
	s_waitcnt lgkmcnt(0)
	v_mfma_f32_32x32x16_bf16 v[96:111], v[2:5], v[152:155], v[96:111]
	ds_read_b64 v[8:9], v221 offset:16384
	ds_read_b64 v[10:11], v222 offset:16384
	ds_read_b64 v[12:13], v221 offset:20480
	ds_read_b64 v[14:15], v222 offset:20480
	ds_read_b64 v[236:237], v221 offset:28672
	ds_read_b64 v[238:239], v222 offset:28672
	s_nop 3
	v_exp_f32_e32 v112, v112
	v_exp_f32_e32 v113, v113
	v_exp_f32_e32 v114, v114
	v_exp_f32_e32 v115, v115
	v_exp_f32_e32 v116, v116
	v_exp_f32_e32 v117, v117
	v_exp_f32_e32 v118, v118
	v_exp_f32_e32 v119, v119
	v_bfe_i32 v231, v229, 0, 1
	v_and_b32_e32 v112, v112, v231
	v_bfe_i32 v232, v229, 1, 1
	v_and_b32_e32 v113, v113, v232
	v_bfe_i32 v231, v229, 2, 1
	v_and_b32_e32 v114, v114, v231
	v_bfe_i32 v232, v229, 3, 1
	v_and_b32_e32 v115, v115, v232
	v_bfe_i32 v231, v229, 8, 1
	v_and_b32_e32 v116, v116, v231
	v_bfe_i32 v232, v229, 9, 1
	v_and_b32_e32 v117, v117, v232
	v_bfe_i32 v231, v229, 10, 1
	v_and_b32_e32 v118, v118, v231
	v_bfe_i32 v232, v229, 11, 1
	v_and_b32_e32 v119, v119, v232
	v_cvt_pk_bf16_f32 v2, v112, v113
	v_cvt_pk_bf16_f32 v3, v114, v115
	v_cvt_pk_bf16_f32 v4, v116, v117
	v_cvt_pk_bf16_f32 v5, v118, v119
	v_pk_add_f32 v[248:249], v[112:113], v[114:115]
	v_pk_add_f32 v[248:249], v[116:117], v[248:249]
	v_pk_add_f32 v[248:249], v[118:119], v[248:249]
	ds_read_b64 v[240:241], v221 offset:24576
	ds_read_b64 v[242:243], v222 offset:24576
	ds_read_b64 v[244:245], v223 offset:16384
	ds_read_b64 v[246:247], v224 offset:16384
	s_waitcnt lgkmcnt(8)
	v_mfma_f32_32x32x16_bf16 v[80:95], v[8:11], v[2:5], v[80:95]
	ds_read_b64 v[112:113], v223 offset:20480
	ds_read_b64 v[114:115], v224 offset:20480
	v_exp_f32_e32 v120, v120
	v_exp_f32_e32 v121, v121
	s_waitcnt lgkmcnt(8)
	v_mfma_f32_32x32x16_bf16 v[64:79], v[12:15], v[2:5], v[64:79]
	ds_read_b64 v[116:117], v223 offset:24576
	ds_read_b64 v[118:119], v224 offset:24576
	v_exp_f32_e32 v122, v122
	v_exp_f32_e32 v123, v123
	v_bfe_i32 v231, v229, 16, 1
	v_and_b32_e32 v120, v120, v231
	v_bfe_i32 v232, v229, 17, 1
	v_and_b32_e32 v121, v121, v232
	v_pk_add_f32 v[248:249], v[120:121], v[248:249]
	s_waitcnt lgkmcnt(8)
	v_mfma_f32_32x32x16_bf16 v[32:47], v[236:239], v[2:5], v[32:47]
	ds_read_b64 v[8:9], v223 offset:28672
	ds_read_b64 v[10:11], v224 offset:28672
	v_exp_f32_e32 v124, v124
	v_exp_f32_e32 v125, v125
	v_bfe_i32 v231, v229, 18, 1
	v_and_b32_e32 v122, v122, v231
	v_bfe_i32 v232, v229, 19, 1
	v_and_b32_e32 v123, v123, v232
	v_pk_add_f32 v[248:249], v[122:123], v[248:249]
	s_waitcnt lgkmcnt(8)
	v_mfma_f32_32x32x16_bf16 v[48:63], v[240:243], v[2:5], v[48:63]
	ds_read_b64 v[12:13], v225 offset:16384
	ds_read_b64 v[14:15], v226 offset:16384
	v_exp_f32_e32 v126, v126
	v_exp_f32_e32 v127, v127
	v_bfe_i32 v231, v229, 24, 1
	v_and_b32_e32 v124, v124, v231
	v_bfe_i32 v232, v229, 25, 1
	v_and_b32_e32 v125, v125, v232
	v_pk_add_f32 v[248:249], v[124:125], v[248:249]
	v_bfe_i32 v231, v229, 26, 1
	v_and_b32_e32 v126, v126, v231
	v_bfe_i32 v232, v229, 27, 1
	v_and_b32_e32 v127, v127, v232
	v_pk_add_f32 v[248:249], v[126:127], v[248:249]
	v_cvt_pk_bf16_f32 v2, v120, v121
	v_cvt_pk_bf16_f32 v3, v122, v123
	v_cvt_pk_bf16_f32 v4, v124, v125
	v_cvt_pk_bf16_f32 v5, v126, v127
	s_nop 1
	ds_read_b64 v[236:237], v225 offset:20480
	ds_read_b64 v[238:239], v226 offset:20480
	s_waitcnt lgkmcnt(10)
	v_mfma_f32_32x32x16_bf16 v[80:95], v[244:247], v[2:5], v[80:95]
	ds_read_b64 v[240:241], v225 offset:24576
	ds_read_b64 v[242:243], v226 offset:24576
	v_exp_f32_e32 v96, v96
	v_exp_f32_e32 v97, v97
	s_waitcnt lgkmcnt(10)
	v_mfma_f32_32x32x16_bf16 v[64:79], v[112:115], v[2:5], v[64:79]
	ds_read_b64 v[120:121], v225 offset:28672
	ds_read_b64 v[122:123], v226 offset:28672
	v_exp_f32_e32 v98, v98
	v_exp_f32_e32 v99, v99
	v_bfe_i32 v231, v230, 0, 1
	v_and_b32_e32 v96, v96, v231
	v_bfe_i32 v232, v230, 1, 1
	v_and_b32_e32 v97, v97, v232
	v_pk_add_f32 v[248:249], v[96:97], v[248:249]
	s_waitcnt lgkmcnt(10)
	v_mfma_f32_32x32x16_bf16 v[48:63], v[116:119], v[2:5], v[48:63]
	ds_read_b64 v[124:125], v227 offset:16384
	ds_read_b64 v[126:127], v228 offset:16384
	v_exp_f32_e32 v100, v100
	v_exp_f32_e32 v101, v101
	v_bfe_i32 v231, v230, 2, 1
	v_and_b32_e32 v98, v98, v231
	v_bfe_i32 v232, v230, 3, 1
	v_and_b32_e32 v99, v99, v232
	v_pk_add_f32 v[248:249], v[98:99], v[248:249]
	s_waitcnt lgkmcnt(10)
	v_mfma_f32_32x32x16_bf16 v[32:47], v[8:11], v[2:5], v[32:47]
	ds_read_b64 v[244:245], v227 offset:20480
	ds_read_b64 v[246:247], v228 offset:20480
	v_exp_f32_e32 v102, v102
	v_exp_f32_e32 v103, v103
	v_bfe_i32 v231, v230, 8, 1
	v_and_b32_e32 v100, v100, v231
	v_bfe_i32 v232, v230, 9, 1
	v_and_b32_e32 v101, v101, v232
	v_pk_add_f32 v[248:249], v[100:101], v[248:249]
	v_bfe_i32 v231, v230, 10, 1
	v_and_b32_e32 v102, v102, v231
	v_bfe_i32 v232, v230, 11, 1
	v_and_b32_e32 v103, v103, v232
	v_pk_add_f32 v[248:249], v[102:103], v[248:249]
	v_cvt_pk_bf16_f32 v2, v96, v97
	v_cvt_pk_bf16_f32 v3, v98, v99
	v_cvt_pk_bf16_f32 v4, v100, v101
	v_cvt_pk_bf16_f32 v5, v102, v103
	s_nop 1
	ds_read_b64 v[112:113], v227 offset:24576
	ds_read_b64 v[114:115], v228 offset:24576
	s_waitcnt lgkmcnt(12)
	v_mfma_f32_32x32x16_bf16 v[80:95], v[12:15], v[2:5], v[80:95]
	ds_read_b64 v[116:117], v227 offset:28672
	ds_read_b64 v[118:119], v228 offset:28672
	v_exp_f32_e32 v104, v104
	v_exp_f32_e32 v105, v105
	s_waitcnt lgkmcnt(12)
	v_mfma_f32_32x32x16_bf16 v[64:79], v[236:239], v[2:5], v[64:79]
	v_exp_f32_e32 v106, v106
	v_exp_f32_e32 v107, v107
	v_bfe_i32 v231, v230, 16, 1
	v_and_b32_e32 v104, v104, v231
	v_bfe_i32 v232, v230, 17, 1
	v_and_b32_e32 v105, v105, v232
	v_pk_add_f32 v[248:249], v[104:105], v[248:249]
	s_waitcnt lgkmcnt(10)
	v_mfma_f32_32x32x16_bf16 v[48:63], v[240:243], v[2:5], v[48:63]
	v_exp_f32_e32 v108, v108
	v_exp_f32_e32 v109, v109
	v_bfe_i32 v231, v230, 18, 1
	v_and_b32_e32 v106, v106, v231
	v_bfe_i32 v232, v230, 19, 1
	v_and_b32_e32 v107, v107, v232
	v_pk_add_f32 v[248:249], v[106:107], v[248:249]
	s_waitcnt lgkmcnt(8)
	v_mfma_f32_32x32x16_bf16 v[32:47], v[120:123], v[2:5], v[32:47]
	v_exp_f32_e32 v110, v110
	v_exp_f32_e32 v111, v111
	v_bfe_i32 v231, v230, 24, 1
	v_and_b32_e32 v108, v108, v231
	v_bfe_i32 v232, v230, 25, 1
	v_and_b32_e32 v109, v109, v232
	v_pk_add_f32 v[248:249], v[108:109], v[248:249]
	v_bfe_i32 v231, v230, 26, 1
	v_and_b32_e32 v110, v110, v231
	v_bfe_i32 v232, v230, 27, 1
	v_and_b32_e32 v111, v111, v232
	v_pk_add_f32 v[248:249], v[110:111], v[248:249]
	v_cvt_pk_bf16_f32 v2, v104, v105
	v_cvt_pk_bf16_f32 v3, v106, v107
	v_cvt_pk_bf16_f32 v4, v108, v109
	v_cvt_pk_bf16_f32 v5, v110, v111
	s_nop 1
	s_waitcnt lgkmcnt(6)
	v_mfma_f32_32x32x16_bf16 v[80:95], v[124:127], v[2:5], v[80:95]
	s_waitcnt lgkmcnt(4)
	v_mfma_f32_32x32x16_bf16 v[64:79], v[244:247], v[2:5], v[64:79]
	s_waitcnt lgkmcnt(2)
	v_mfma_f32_32x32x16_bf16 v[48:63], v[112:115], v[2:5], v[48:63]
	s_waitcnt lgkmcnt(0)
	v_mfma_f32_32x32x16_bf16 v[32:47], v[116:119], v[2:5], v[32:47]
	v_add_f32_e32 v0, v248, v249
	v_add_f32_e32 v219, v219, v0

.LBB0_1371:
	s_or_b64 exec, exec, s[22:23]
	v_cmp_le_i32_e32 vcc, s34, v226
	s_and_saveexec_b64 s[22:23], vcc
	s_cbranch_execz .LBB0_1373
	ds_read_b64 v[6:7], v228 offset:8192
	ds_read_b64 v[8:9], v229 offset:8192
	ds_read_b64 v[10:11], v230 offset:20480
	ds_read_b64 v[12:13], v231 offset:20480
	ds_read_b64 v[244:245], v230 offset:12288
	ds_read_b64 v[246:247], v231 offset:12288
	v_exp_f32_e32 v32, v32
	v_exp_f32_e32 v33, v33
	v_exp_f32_e32 v34, v34
	v_exp_f32_e32 v35, v35
	v_exp_f32_e32 v36, v36
	v_exp_f32_e32 v37, v37
	v_exp_f32_e32 v38, v38
	v_exp_f32_e32 v39, v39
	v_cvt_pk_bf16_f32 v2, v32, v33
	v_cvt_pk_bf16_f32 v3, v34, v35
	v_cvt_pk_bf16_f32 v4, v36, v37
	v_cvt_pk_bf16_f32 v5, v38, v39
	v_pk_add_f32 v[248:249], v[32:33], v[34:35]
	v_pk_add_f32 v[248:249], v[36:37], v[248:249]
	v_pk_add_f32 v[248:249], v[38:39], v[248:249]
	ds_read_b64 v[32:33], v230 offset:16384
	ds_read_b64 v[34:35], v231 offset:16384
	ds_read_b64 v[36:37], v232 offset:8192
	ds_read_b64 v[38:39], v233 offset:8192
	s_waitcnt lgkmcnt(8)
	v_mfma_f32_32x32x16_bf16 v[112:127], v[6:9], v[2:5], v[112:127]
	ds_read_b64 v[6:7], v234 offset:20480
	ds_read_b64 v[8:9], v235 offset:20480
	v_exp_f32_e32 v40, v40
	v_exp_f32_e32 v41, v41
	s_waitcnt lgkmcnt(8)
	v_mfma_f32_32x32x16_bf16 v[64:79], v[10:13], v[2:5], v[64:79]
	ds_read_b64 v[10:11], v234 offset:12288
	ds_read_b64 v[12:13], v235 offset:12288
	v_exp_f32_e32 v42, v42
	v_exp_f32_e32 v43, v43
	v_pk_add_f32 v[248:249], v[40:41], v[248:249]
	s_waitcnt lgkmcnt(8)
	v_mfma_f32_32x32x16_bf16 v[96:111], v[244:247], v[2:5], v[96:111]
	ds_read_b64 v[244:245], v234 offset:16384
	ds_read_b64 v[246:247], v235 offset:16384
	v_exp_f32_e32 v44, v44
	v_exp_f32_e32 v45, v45
	v_pk_add_f32 v[248:249], v[42:43], v[248:249]
	s_waitcnt lgkmcnt(8)
	v_mfma_f32_32x32x16_bf16 v[80:95], v[32:35], v[2:5], v[80:95]
	ds_read_b64 v[32:33], v236 offset:8192
	ds_read_b64 v[34:35], v237 offset:8192
	v_exp_f32_e32 v46, v46
	v_exp_f32_e32 v47, v47
	v_pk_add_f32 v[248:249], v[44:45], v[248:249]
	v_pk_add_f32 v[248:249], v[46:47], v[248:249]
	v_cvt_pk_bf16_f32 v2, v40, v41
	v_cvt_pk_bf16_f32 v3, v42, v43
	v_cvt_pk_bf16_f32 v4, v44, v45
	v_cvt_pk_bf16_f32 v5, v46, v47
	s_nop 1
	ds_read_b64 v[40:41], v238 offset:20480
	ds_read_b64 v[42:43], v239 offset:20480
	s_waitcnt lgkmcnt(10)
	v_mfma_f32_32x32x16_bf16 v[112:127], v[36:39], v[2:5], v[112:127]
	ds_read_b64 v[44:45], v238 offset:12288
	ds_read_b64 v[46:47], v239 offset:12288
	v_exp_f32_e32 v48, v48
	v_exp_f32_e32 v49, v49
	s_waitcnt lgkmcnt(10)
	v_mfma_f32_32x32x16_bf16 v[64:79], v[6:9], v[2:5], v[64:79]
	ds_read_b64 v[36:37], v238 offset:16384
	ds_read_b64 v[38:39], v239 offset:16384
	v_exp_f32_e32 v50, v50
	v_exp_f32_e32 v51, v51
	v_pk_add_f32 v[248:249], v[48:49], v[248:249]
	s_waitcnt lgkmcnt(10)
	v_mfma_f32_32x32x16_bf16 v[96:111], v[10:13], v[2:5], v[96:111]
	ds_read_b64 v[6:7], v240 offset:8192
	ds_read_b64 v[8:9], v241 offset:8192
	v_exp_f32_e32 v52, v52
	v_exp_f32_e32 v53, v53
	v_pk_add_f32 v[248:249], v[50:51], v[248:249]
	s_waitcnt lgkmcnt(10)
	v_mfma_f32_32x32x16_bf16 v[80:95], v[244:247], v[2:5], v[80:95]
	ds_read_b64 v[10:11], v242 offset:12288
	ds_read_b64 v[12:13], v243 offset:12288
	v_exp_f32_e32 v54, v54
	v_exp_f32_e32 v55, v55
	v_pk_add_f32 v[248:249], v[52:53], v[248:249]
	v_pk_add_f32 v[248:249], v[54:55], v[248:249]
	v_cvt_pk_bf16_f32 v2, v48, v49
	v_cvt_pk_bf16_f32 v3, v50, v51
	v_cvt_pk_bf16_f32 v4, v52, v53
	v_cvt_pk_bf16_f32 v5, v54, v55
	s_nop 1
	ds_read_b64 v[244:245], v242 offset:16384
	ds_read_b64 v[246:247], v243 offset:16384
	s_waitcnt lgkmcnt(12)
	v_mfma_f32_32x32x16_bf16 v[112:127], v[32:35], v[2:5], v[112:127]
	ds_read_b64 v[48:49], v242 offset:20480
	ds_read_b64 v[50:51], v243 offset:20480
	v_exp_f32_e32 v56, v56
	v_exp_f32_e32 v57, v57
	s_waitcnt lgkmcnt(12)
	v_mfma_f32_32x32x16_bf16 v[64:79], v[40:43], v[2:5], v[64:79]
	v_exp_f32_e32 v58, v58
	v_exp_f32_e32 v59, v59
	v_pk_add_f32 v[248:249], v[56:57], v[248:249]
	s_waitcnt lgkmcnt(10)
	v_mfma_f32_32x32x16_bf16 v[96:111], v[44:47], v[2:5], v[96:111]
	v_exp_f32_e32 v60, v60
	v_exp_f32_e32 v61, v61
	v_pk_add_f32 v[248:249], v[58:59], v[248:249]
	s_waitcnt lgkmcnt(8)
	v_mfma_f32_32x32x16_bf16 v[80:95], v[36:39], v[2:5], v[80:95]
	v_exp_f32_e32 v62, v62
	v_exp_f32_e32 v63, v63
	v_pk_add_f32 v[248:249], v[60:61], v[248:249]
	v_pk_add_f32 v[248:249], v[62:63], v[248:249]
	v_cvt_pk_bf16_f32 v2, v56, v57
	v_cvt_pk_bf16_f32 v3, v58, v59
	v_cvt_pk_bf16_f32 v4, v60, v61
	v_cvt_pk_bf16_f32 v5, v62, v63
	s_nop 1
	s_waitcnt lgkmcnt(6)
	v_mfma_f32_32x32x16_bf16 v[112:127], v[6:9], v[2:5], v[112:127]
	s_waitcnt lgkmcnt(4)
	v_mfma_f32_32x32x16_bf16 v[96:111], v[10:13], v[2:5], v[96:111]
	s_waitcnt lgkmcnt(2)
	v_mfma_f32_32x32x16_bf16 v[80:95], v[244:247], v[2:5], v[80:95]
	s_waitcnt lgkmcnt(0)
	v_mfma_f32_32x32x16_bf16 v[64:79], v[48:51], v[2:5], v[64:79]
	v_add_f32_e32 v0, v248, v249
	v_add_f32_e32 v227, v227, v0

.LBB0_1385:
	ds_read_b64 v[6:7], v228 offset:32768
	ds_read_b64 v[8:9], v229 offset:32768
	ds_read_b64 v[10:11], v230 offset:45056
	ds_read_b64 v[12:13], v231 offset:45056
	ds_read_b64 v[244:245], v230 offset:36864
	ds_read_b64 v[246:247], v231 offset:36864
	v_exp_f32_e32 v128, v128
	v_exp_f32_e32 v129, v129
	v_exp_f32_e32 v130, v130
	v_exp_f32_e32 v131, v131
	v_exp_f32_e32 v132, v132
	v_exp_f32_e32 v133, v133
	v_exp_f32_e32 v134, v134
	v_exp_f32_e32 v135, v135
	v_cvt_pk_bf16_f32 v2, v128, v129
	v_cvt_pk_bf16_f32 v3, v130, v131
	v_cvt_pk_bf16_f32 v4, v132, v133
	v_cvt_pk_bf16_f32 v5, v134, v135
	v_pk_add_f32 v[248:249], v[128:129], v[130:131]
	v_pk_add_f32 v[248:249], v[132:133], v[248:249]
	v_pk_add_f32 v[248:249], v[134:135], v[248:249]
	ds_read_b64 v[128:129], v230 offset:40960
	ds_read_b64 v[130:131], v231 offset:40960
	ds_read_b64 v[132:133], v232 offset:32768
	ds_read_b64 v[134:135], v233 offset:32768
	s_waitcnt lgkmcnt(8)
	v_mfma_f32_32x32x16_bf16 v[112:127], v[6:9], v[2:5], v[112:127]
	ds_read_b64 v[6:7], v234 offset:45056
	ds_read_b64 v[8:9], v235 offset:45056
	v_exp_f32_e32 v136, v136
	v_exp_f32_e32 v137, v137
	s_waitcnt lgkmcnt(8)
	v_mfma_f32_32x32x16_bf16 v[64:79], v[10:13], v[2:5], v[64:79]
	ds_read_b64 v[10:11], v234 offset:36864
	ds_read_b64 v[12:13], v235 offset:36864
	v_exp_f32_e32 v138, v138
	v_exp_f32_e32 v139, v139
	v_pk_add_f32 v[248:249], v[136:137], v[248:249]
	s_waitcnt lgkmcnt(8)
	v_mfma_f32_32x32x16_bf16 v[96:111], v[244:247], v[2:5], v[96:111]
	ds_read_b64 v[244:245], v234 offset:40960
	ds_read_b64 v[246:247], v235 offset:40960
	v_exp_f32_e32 v140, v140
	v_exp_f32_e32 v141, v141
	v_pk_add_f32 v[248:249], v[138:139], v[248:249]
	s_waitcnt lgkmcnt(8)
	v_mfma_f32_32x32x16_bf16 v[80:95], v[128:131], v[2:5], v[80:95]
	ds_read_b64 v[128:129], v236 offset:32768
	ds_read_b64 v[130:131], v237 offset:32768
	v_exp_f32_e32 v142, v142
	v_exp_f32_e32 v143, v143
	v_pk_add_f32 v[248:249], v[140:141], v[248:249]
	v_pk_add_f32 v[248:249], v[142:143], v[248:249]
	v_cvt_pk_bf16_f32 v2, v136, v137
	v_cvt_pk_bf16_f32 v3, v138, v139
	v_cvt_pk_bf16_f32 v4, v140, v141
	v_cvt_pk_bf16_f32 v5, v142, v143
	s_nop 1
	ds_read_b64 v[136:137], v238 offset:45056
	ds_read_b64 v[138:139], v239 offset:45056
	s_waitcnt lgkmcnt(10)
	v_mfma_f32_32x32x16_bf16 v[112:127], v[132:135], v[2:5], v[112:127]
	ds_read_b64 v[140:141], v238 offset:36864
	ds_read_b64 v[142:143], v239 offset:36864
	v_exp_f32_e32 v144, v144
	v_exp_f32_e32 v145, v145
	s_waitcnt lgkmcnt(10)
	v_mfma_f32_32x32x16_bf16 v[64:79], v[6:9], v[2:5], v[64:79]
	ds_read_b64 v[132:133], v238 offset:40960
	ds_read_b64 v[134:135], v239 offset:40960
	v_exp_f32_e32 v146, v146
	v_exp_f32_e32 v147, v147
	v_pk_add_f32 v[248:249], v[144:145], v[248:249]
	s_waitcnt lgkmcnt(10)
	v_mfma_f32_32x32x16_bf16 v[96:111], v[10:13], v[2:5], v[96:111]
	ds_read_b64 v[6:7], v240 offset:32768
	ds_read_b64 v[8:9], v241 offset:32768
	v_exp_f32_e32 v148, v148
	v_exp_f32_e32 v149, v149
	v_pk_add_f32 v[248:249], v[146:147], v[248:249]
	s_waitcnt lgkmcnt(10)
	v_mfma_f32_32x32x16_bf16 v[80:95], v[244:247], v[2:5], v[80:95]
	ds_read_b64 v[10:11], v242 offset:36864
	ds_read_b64 v[12:13], v243 offset:36864
	v_exp_f32_e32 v150, v150
	v_exp_f32_e32 v151, v151
	v_pk_add_f32 v[248:249], v[148:149], v[248:249]
	v_pk_add_f32 v[248:249], v[150:151], v[248:249]
	v_cvt_pk_bf16_f32 v2, v144, v145
	v_cvt_pk_bf16_f32 v3, v146, v147
	v_cvt_pk_bf16_f32 v4, v148, v149
	v_cvt_pk_bf16_f32 v5, v150, v151
	s_nop 1
	ds_read_b64 v[244:245], v242 offset:40960
	ds_read_b64 v[246:247], v243 offset:40960
	s_waitcnt lgkmcnt(12)
	v_mfma_f32_32x32x16_bf16 v[112:127], v[128:131], v[2:5], v[112:127]
	ds_read_b64 v[144:145], v242 offset:45056
	ds_read_b64 v[146:147], v243 offset:45056
	v_exp_f32_e32 v152, v152
	v_exp_f32_e32 v153, v153
	s_waitcnt lgkmcnt(12)
	v_mfma_f32_32x32x16_bf16 v[64:79], v[136:139], v[2:5], v[64:79]
	v_exp_f32_e32 v154, v154
	v_exp_f32_e32 v155, v155
	v_pk_add_f32 v[248:249], v[152:153], v[248:249]
	s_waitcnt lgkmcnt(10)
	v_mfma_f32_32x32x16_bf16 v[96:111], v[140:143], v[2:5], v[96:111]
	v_exp_f32_e32 v156, v156
	v_exp_f32_e32 v157, v157
	v_pk_add_f32 v[248:249], v[154:155], v[248:249]
	s_waitcnt lgkmcnt(8)
	v_mfma_f32_32x32x16_bf16 v[80:95], v[132:135], v[2:5], v[80:95]
	v_exp_f32_e32 v158, v158
	v_exp_f32_e32 v159, v159
	v_pk_add_f32 v[248:249], v[156:157], v[248:249]
	v_pk_add_f32 v[248:249], v[158:159], v[248:249]
	v_cvt_pk_bf16_f32 v2, v152, v153
	v_cvt_pk_bf16_f32 v3, v154, v155
	v_cvt_pk_bf16_f32 v4, v156, v157
	v_cvt_pk_bf16_f32 v5, v158, v159
	s_nop 1
	s_waitcnt lgkmcnt(6)
	v_mfma_f32_32x32x16_bf16 v[112:127], v[6:9], v[2:5], v[112:127]
	s_waitcnt lgkmcnt(4)
	v_mfma_f32_32x32x16_bf16 v[96:111], v[10:13], v[2:5], v[96:111]
	s_waitcnt lgkmcnt(2)
	v_mfma_f32_32x32x16_bf16 v[80:95], v[244:247], v[2:5], v[80:95]
	s_waitcnt lgkmcnt(0)
	v_mfma_f32_32x32x16_bf16 v[64:79], v[144:147], v[2:5], v[64:79]
	v_add_f32_e32 v0, v248, v249
	v_add_f32_e32 v227, v0, v227

.LBB0_1413:
	s_or_b64 exec, exec, s[22:23]
	v_cmp_le_i32_e32 vcc, s31, v225
	s_and_saveexec_b64 s[22:23], vcc
	s_cbranch_execz .LBB0_1415
	ds_read_b64 v[6:7], v226 offset:8192
	ds_read_b64 v[8:9], v227 offset:8192
	ds_read_b64 v[10:11], v228 offset:20480
	ds_read_b64 v[12:13], v229 offset:20480
	ds_read_b64 v[242:243], v228 offset:12288
	ds_read_b64 v[244:245], v229 offset:12288
	v_exp_f32_e32 v80, v80
	v_exp_f32_e32 v81, v81
	v_exp_f32_e32 v82, v82
	v_exp_f32_e32 v83, v83
	v_exp_f32_e32 v84, v84
	v_exp_f32_e32 v85, v85
	v_exp_f32_e32 v86, v86
	v_exp_f32_e32 v87, v87
	v_cvt_pk_bf16_f32 v2, v80, v81
	v_cvt_pk_bf16_f32 v3, v82, v83
	v_cvt_pk_bf16_f32 v4, v84, v85
	v_cvt_pk_bf16_f32 v5, v86, v87
	v_pk_add_f32 v[248:249], v[80:81], v[82:83]
	v_pk_add_f32 v[248:249], v[84:85], v[248:249]
	v_pk_add_f32 v[248:249], v[86:87], v[248:249]
	ds_read_b64 v[80:81], v228 offset:16384
	ds_read_b64 v[82:83], v229 offset:16384
	ds_read_b64 v[84:85], v230 offset:8192
	ds_read_b64 v[86:87], v231 offset:8192
	s_waitcnt lgkmcnt(8)
	v_mfma_f32_32x32x16_bf16 v[64:79], v[6:9], v[2:5], v[64:79]
	ds_read_b64 v[6:7], v232 offset:20480
	ds_read_b64 v[8:9], v233 offset:20480
	v_exp_f32_e32 v88, v88
	v_exp_f32_e32 v89, v89
	s_waitcnt lgkmcnt(8)
	v_mfma_f32_32x32x16_bf16 v[112:127], v[10:13], v[2:5], v[112:127]
	ds_read_b64 v[10:11], v232 offset:12288
	ds_read_b64 v[12:13], v233 offset:12288
	v_exp_f32_e32 v90, v90
	v_exp_f32_e32 v91, v91
	v_pk_add_f32 v[248:249], v[88:89], v[248:249]
	s_waitcnt lgkmcnt(8)
	v_mfma_f32_32x32x16_bf16 v[48:63], v[242:245], v[2:5], v[48:63]
	ds_read_b64 v[242:243], v232 offset:16384
	ds_read_b64 v[244:245], v233 offset:16384
	v_exp_f32_e32 v92, v92
	v_exp_f32_e32 v93, v93
	v_pk_add_f32 v[248:249], v[90:91], v[248:249]
	s_waitcnt lgkmcnt(8)
	v_mfma_f32_32x32x16_bf16 v[32:47], v[80:83], v[2:5], v[32:47]
	ds_read_b64 v[80:81], v234 offset:8192
	ds_read_b64 v[82:83], v235 offset:8192
	v_exp_f32_e32 v94, v94
	v_exp_f32_e32 v95, v95
	v_pk_add_f32 v[248:249], v[92:93], v[248:249]
	v_pk_add_f32 v[248:249], v[94:95], v[248:249]
	v_cvt_pk_bf16_f32 v2, v88, v89
	v_cvt_pk_bf16_f32 v3, v90, v91
	v_cvt_pk_bf16_f32 v4, v92, v93
	v_cvt_pk_bf16_f32 v5, v94, v95
	s_nop 1
	ds_read_b64 v[88:89], v236 offset:20480
	ds_read_b64 v[90:91], v237 offset:20480
	s_waitcnt lgkmcnt(10)
	v_mfma_f32_32x32x16_bf16 v[64:79], v[84:87], v[2:5], v[64:79]
	ds_read_b64 v[92:93], v236 offset:12288
	ds_read_b64 v[94:95], v237 offset:12288
	v_exp_f32_e32 v96, v96
	v_exp_f32_e32 v97, v97
	s_waitcnt lgkmcnt(10)
	v_mfma_f32_32x32x16_bf16 v[112:127], v[6:9], v[2:5], v[112:127]
	ds_read_b64 v[84:85], v236 offset:16384
	ds_read_b64 v[86:87], v237 offset:16384
	v_exp_f32_e32 v98, v98
	v_exp_f32_e32 v99, v99
	v_pk_add_f32 v[248:249], v[96:97], v[248:249]
	s_waitcnt lgkmcnt(10)
	v_mfma_f32_32x32x16_bf16 v[48:63], v[10:13], v[2:5], v[48:63]
	ds_read_b64 v[6:7], v238 offset:8192
	ds_read_b64 v[8:9], v239 offset:8192
	v_exp_f32_e32 v100, v100
	v_exp_f32_e32 v101, v101
	v_pk_add_f32 v[248:249], v[98:99], v[248:249]
	s_waitcnt lgkmcnt(10)
	v_mfma_f32_32x32x16_bf16 v[32:47], v[242:245], v[2:5], v[32:47]
	ds_read_b64 v[10:11], v240 offset:12288
	ds_read_b64 v[12:13], v241 offset:12288
	v_exp_f32_e32 v102, v102
	v_exp_f32_e32 v103, v103
	v_pk_add_f32 v[248:249], v[100:101], v[248:249]
	v_pk_add_f32 v[248:249], v[102:103], v[248:249]
	v_cvt_pk_bf16_f32 v2, v96, v97
	v_cvt_pk_bf16_f32 v3, v98, v99
	v_cvt_pk_bf16_f32 v4, v100, v101
	v_cvt_pk_bf16_f32 v5, v102, v103
	s_nop 1
	ds_read_b64 v[242:243], v240 offset:16384
	ds_read_b64 v[244:245], v241 offset:16384
	s_waitcnt lgkmcnt(12)
	v_mfma_f32_32x32x16_bf16 v[64:79], v[80:83], v[2:5], v[64:79]
	ds_read_b64 v[96:97], v240 offset:20480
	ds_read_b64 v[98:99], v241 offset:20480
	v_exp_f32_e32 v104, v104
	v_exp_f32_e32 v105, v105
	s_waitcnt lgkmcnt(12)
	v_mfma_f32_32x32x16_bf16 v[112:127], v[88:91], v[2:5], v[112:127]
	v_exp_f32_e32 v106, v106
	v_exp_f32_e32 v107, v107
	v_pk_add_f32 v[248:249], v[104:105], v[248:249]
	s_waitcnt lgkmcnt(10)
	v_mfma_f32_32x32x16_bf16 v[48:63], v[92:95], v[2:5], v[48:63]
	v_exp_f32_e32 v108, v108
	v_exp_f32_e32 v109, v109
	v_pk_add_f32 v[248:249], v[106:107], v[248:249]
	s_waitcnt lgkmcnt(8)
	v_mfma_f32_32x32x16_bf16 v[32:47], v[84:87], v[2:5], v[32:47]
	v_exp_f32_e32 v110, v110
	v_exp_f32_e32 v111, v111
	v_pk_add_f32 v[248:249], v[108:109], v[248:249]
	v_pk_add_f32 v[248:249], v[110:111], v[248:249]
	v_cvt_pk_bf16_f32 v2, v104, v105
	v_cvt_pk_bf16_f32 v3, v106, v107
	v_cvt_pk_bf16_f32 v4, v108, v109
	v_cvt_pk_bf16_f32 v5, v110, v111
	s_nop 1
	s_waitcnt lgkmcnt(6)
	v_mfma_f32_32x32x16_bf16 v[64:79], v[6:9], v[2:5], v[64:79]
	s_waitcnt lgkmcnt(4)
	v_mfma_f32_32x32x16_bf16 v[48:63], v[10:13], v[2:5], v[48:63]
	s_waitcnt lgkmcnt(2)
	v_mfma_f32_32x32x16_bf16 v[32:47], v[242:245], v[2:5], v[32:47]
	s_waitcnt lgkmcnt(0)
	v_mfma_f32_32x32x16_bf16 v[112:127], v[96:99], v[2:5], v[112:127]
	v_add_f32_e32 v0, v248, v249
	v_add_f32_e32 v224, v224, v0

.LBB0_1427:
	ds_read_b64 v[6:7], v226 offset:32768
	ds_read_b64 v[8:9], v227 offset:32768
	ds_read_b64 v[10:11], v228 offset:45056
	ds_read_b64 v[12:13], v229 offset:45056
	ds_read_b64 v[242:243], v228 offset:36864
	ds_read_b64 v[244:245], v229 offset:36864
	v_exp_f32_e32 v128, v128
	v_exp_f32_e32 v129, v129
	v_exp_f32_e32 v130, v130
	v_exp_f32_e32 v131, v131
	v_exp_f32_e32 v132, v132
	v_exp_f32_e32 v133, v133
	v_exp_f32_e32 v134, v134
	v_exp_f32_e32 v135, v135
	v_cvt_pk_bf16_f32 v2, v128, v129
	v_cvt_pk_bf16_f32 v3, v130, v131
	v_cvt_pk_bf16_f32 v4, v132, v133
	v_cvt_pk_bf16_f32 v5, v134, v135
	v_pk_add_f32 v[248:249], v[128:129], v[130:131]
	v_pk_add_f32 v[248:249], v[132:133], v[248:249]
	v_pk_add_f32 v[248:249], v[134:135], v[248:249]
	ds_read_b64 v[128:129], v228 offset:40960
	ds_read_b64 v[130:131], v229 offset:40960
	ds_read_b64 v[132:133], v230 offset:32768
	ds_read_b64 v[134:135], v231 offset:32768
	s_waitcnt lgkmcnt(8)
	v_mfma_f32_32x32x16_bf16 v[64:79], v[6:9], v[2:5], v[64:79]
	ds_read_b64 v[6:7], v232 offset:45056
	ds_read_b64 v[8:9], v233 offset:45056
	v_exp_f32_e32 v136, v136
	v_exp_f32_e32 v137, v137
	s_waitcnt lgkmcnt(8)
	v_mfma_f32_32x32x16_bf16 v[112:127], v[10:13], v[2:5], v[112:127]
	ds_read_b64 v[10:11], v232 offset:36864
	ds_read_b64 v[12:13], v233 offset:36864
	v_exp_f32_e32 v138, v138
	v_exp_f32_e32 v139, v139
	v_pk_add_f32 v[248:249], v[136:137], v[248:249]
	s_waitcnt lgkmcnt(8)
	v_mfma_f32_32x32x16_bf16 v[48:63], v[242:245], v[2:5], v[48:63]
	ds_read_b64 v[242:243], v232 offset:40960
	ds_read_b64 v[244:245], v233 offset:40960
	v_exp_f32_e32 v140, v140
	v_exp_f32_e32 v141, v141
	v_pk_add_f32 v[248:249], v[138:139], v[248:249]
	s_waitcnt lgkmcnt(8)
	v_mfma_f32_32x32x16_bf16 v[32:47], v[128:131], v[2:5], v[32:47]
	ds_read_b64 v[128:129], v234 offset:32768
	ds_read_b64 v[130:131], v235 offset:32768
	v_exp_f32_e32 v142, v142
	v_exp_f32_e32 v143, v143
	v_pk_add_f32 v[248:249], v[140:141], v[248:249]
	v_pk_add_f32 v[248:249], v[142:143], v[248:249]
	v_cvt_pk_bf16_f32 v2, v136, v137
	v_cvt_pk_bf16_f32 v3, v138, v139
	v_cvt_pk_bf16_f32 v4, v140, v141
	v_cvt_pk_bf16_f32 v5, v142, v143
	s_nop 1
	ds_read_b64 v[136:137], v236 offset:45056
	ds_read_b64 v[138:139], v237 offset:45056
	s_waitcnt lgkmcnt(10)
	v_mfma_f32_32x32x16_bf16 v[64:79], v[132:135], v[2:5], v[64:79]
	ds_read_b64 v[140:141], v236 offset:36864
	ds_read_b64 v[142:143], v237 offset:36864
	v_exp_f32_e32 v144, v144
	v_exp_f32_e32 v145, v145
	s_waitcnt lgkmcnt(10)
	v_mfma_f32_32x32x16_bf16 v[112:127], v[6:9], v[2:5], v[112:127]
	ds_read_b64 v[132:133], v236 offset:40960
	ds_read_b64 v[134:135], v237 offset:40960
	v_exp_f32_e32 v146, v146
	v_exp_f32_e32 v147, v147
	v_pk_add_f32 v[248:249], v[144:145], v[248:249]
	s_waitcnt lgkmcnt(10)
	v_mfma_f32_32x32x16_bf16 v[48:63], v[10:13], v[2:5], v[48:63]
	ds_read_b64 v[6:7], v238 offset:32768
	ds_read_b64 v[8:9], v239 offset:32768
	v_exp_f32_e32 v148, v148
	v_exp_f32_e32 v149, v149
	v_pk_add_f32 v[248:249], v[146:147], v[248:249]
	s_waitcnt lgkmcnt(10)
	v_mfma_f32_32x32x16_bf16 v[32:47], v[242:245], v[2:5], v[32:47]
	ds_read_b64 v[10:11], v240 offset:36864
	ds_read_b64 v[12:13], v241 offset:36864
	v_exp_f32_e32 v150, v150
	v_exp_f32_e32 v151, v151
	v_pk_add_f32 v[248:249], v[148:149], v[248:249]
	v_pk_add_f32 v[248:249], v[150:151], v[248:249]
	v_cvt_pk_bf16_f32 v2, v144, v145
	v_cvt_pk_bf16_f32 v3, v146, v147
	v_cvt_pk_bf16_f32 v4, v148, v149
	v_cvt_pk_bf16_f32 v5, v150, v151
	s_nop 1
	ds_read_b64 v[242:243], v240 offset:40960
	ds_read_b64 v[244:245], v241 offset:40960
	s_waitcnt lgkmcnt(12)
	v_mfma_f32_32x32x16_bf16 v[64:79], v[128:131], v[2:5], v[64:79]
	ds_read_b64 v[144:145], v240 offset:45056
	ds_read_b64 v[146:147], v241 offset:45056
	v_exp_f32_e32 v152, v152
	v_exp_f32_e32 v153, v153
	s_waitcnt lgkmcnt(12)
	v_mfma_f32_32x32x16_bf16 v[112:127], v[136:139], v[2:5], v[112:127]
	v_exp_f32_e32 v154, v154
	v_exp_f32_e32 v155, v155
	v_pk_add_f32 v[248:249], v[152:153], v[248:249]
	s_waitcnt lgkmcnt(10)
	v_mfma_f32_32x32x16_bf16 v[48:63], v[140:143], v[2:5], v[48:63]
	v_exp_f32_e32 v156, v156
	v_exp_f32_e32 v157, v157
	v_pk_add_f32 v[248:249], v[154:155], v[248:249]
	s_waitcnt lgkmcnt(8)
	v_mfma_f32_32x32x16_bf16 v[32:47], v[132:135], v[2:5], v[32:47]
	v_exp_f32_e32 v158, v158
	v_exp_f32_e32 v159, v159
	v_pk_add_f32 v[248:249], v[156:157], v[248:249]
	v_pk_add_f32 v[248:249], v[158:159], v[248:249]
	v_cvt_pk_bf16_f32 v2, v152, v153
	v_cvt_pk_bf16_f32 v3, v154, v155
	v_cvt_pk_bf16_f32 v4, v156, v157
	v_cvt_pk_bf16_f32 v5, v158, v159
	s_nop 1
	s_waitcnt lgkmcnt(6)
	v_mfma_f32_32x32x16_bf16 v[64:79], v[6:9], v[2:5], v[64:79]
	s_waitcnt lgkmcnt(4)
	v_mfma_f32_32x32x16_bf16 v[48:63], v[10:13], v[2:5], v[48:63]
	s_waitcnt lgkmcnt(2)
	v_mfma_f32_32x32x16_bf16 v[32:47], v[242:245], v[2:5], v[32:47]
	s_waitcnt lgkmcnt(0)
	v_mfma_f32_32x32x16_bf16 v[112:127], v[144:147], v[2:5], v[112:127]
	v_add_f32_e32 v0, v248, v249
	v_add_f32_e32 v224, v0, v224
